# f16-output GEMM epilogue: per store 8 v_max + 4 v_pk_mul + 4 cvt (relu^2) or 4 cvt straight from the accumulators (plain), instead of 8 copies + 16 v_max + 4 v_pk_mul + 4 cvt
# speedup vs baseline: 1.0095x; 1.0016x over previous
; #define PG8_STAGE(bufoff, gbase, voff) do { _Pragma("unroll") for (int _i = 0; _i < 2; ++_i) \
;         __builtin_amdgcn_global_load_lds((const unsigned*)((const char*)(gbase) + (voff)[_i]), (LAS unsigned*)(lds + (bufoff) + ldsw + _i * 8192), 16, 0, 0); } while (0)
; #define PG8_LDA(dst, b, h) do { _Pragma("unroll") for (int m = 0; m < 4; ++m) _Pragma("unroll") for (int k = 0; k < 2; ++k) dst[m][k] = *(const LAS f16x8*)(lds + PG8_SA(b, h) + aoff + m * 2048 + k * 1024); } while (0)
; #define PG8_LDB(dst, b, h) do { _Pragma("unroll") for (int n = 0; n < 2; ++n) _Pragma("unroll") for (int k = 0; k < 2; ++k) dst[n][k] = *(const LAS f16x8*)(lds + PG8_SB(b, h) + boff + n * 2048 + k * 1024); } while (0)
; #define PG8_MMA(ai, bj, At, Bt) do { __builtin_amdgcn_s_setprio(1); _Pragma("unroll") for (int m = 0; m < 4; ++m) _Pragma("unroll") for (int n = 0; n < 2; ++n) _Pragma("unroll") for (int k = 0; k < 2; ++k) \
;         acc[ai][bj][m][n] = __builtin_amdgcn_mfma_f32_16x16x32_f16(Bt[n][k], At[m][k], acc[ai][bj][m][n], 0, 0, 0); __builtin_amdgcn_s_setprio(0); } while (0)
; #define PG8_WAIT_L(n) asm volatile("s_waitcnt lgkmcnt(" #n ")" ::: "memory")
; #define PG8_BAR __builtin_amdgcn_s_barrier()
; #define PG8_SCHED __builtin_amdgcn_sched_barrier(0)
; template <class Epi, class Sched>
; __device__ __forceinline__ void gemm_phase(LAS unsigned char* lds, const Gemm g, const Sched& S, const Epi& E) {
;     ...
;             PG8_LDB(B0, 0, 0); PG8_SCHED; PG8_LDA(At, 0, 0); PG8_STAGE(PG8_SA(1, 1), a1 + hstep, voffA);
;             PG8_WAIT_L(8); PG8_BAR; PG8_WAIT_L(0); PG8_MMA(0, 0, At, B0); PG8_BAR; PG8_SCHED;
;             PG8_LDB(B1, 0, 1); PG8_STAGE(PG8_SB(0, 0), b2, voffB);
;             PG8_BAR; PG8_WAIT_L(0); PG8_MMA(0, 1, At, B1); PG8_BAR;
;             PG8_LDA(At, 0, 1); PG8_STAGE(PG8_SA(0, 0), a2, voffA);
;             PG8_BAR; PG8_WAIT_L(0); PG8_MMA(1, 0, At, B0); PG8_BAR; PG8_SCHED;
.LBB0_829:
	s_add_i32 vcc_hi, s8, 2
	s_add_u32 s10, s6, 0x80
	s_addc_u32 s9, s7, 0
	s_add_i32 s17, 0, 0x10000
	v_add_u32_e32 v16, s17, v159
	ds_read_b128 v[144:147], v16
	ds_read_b128 v[148:151], v16 offset:1024
	ds_read_b128 v[152:155], v16 offset:2048
	ds_read_b128 v[162:165], v16 offset:3072
	s_cmp_eq_u32 s40, s8
	s_cselect_b32 s8, s66, s10
	s_cselect_b32 s9, s67, s9
	s_cselect_b32 s11, s69, vcc_lo
	s_cselect_b32 s10, s68, s41
	v_lshl_add_u64 v[156:157], s[6:7], 0, v[140:141]
	s_add_i32 m0, s82, 0xc000
	ds_read_b128 v[166:169], v161
	ds_read_b128 v[170:173], v161 offset:1024
	ds_read_b128 v[174:177], v161 offset:2048
	ds_read_b128 v[178:181], v161 offset:3072
	ds_read_b128 v[182:185], v161 offset:4096
	ds_read_b128 v[186:189], v161 offset:5120
	ds_read_b128 v[190:193], v161 offset:6144
	ds_read_b128 v[194:197], v161 offset:7168
	global_load_lds_dwordx4 v[156:157], off
	v_lshl_add_u64 v[156:157], s[6:7], 0, v[142:143]
	s_add_i32 m0, s82, 0xe000
	s_nop 0
	global_load_lds_dwordx4 v[156:157], off
	s_waitcnt lgkmcnt(8)
	s_barrier
	s_waitcnt lgkmcnt(0)
	s_setprio 1
	s_waitcnt lgkmcnt(0)
	v_mfma_f32_16x16x32_f16 v[126:129], v[144:147], v[166:169], v[126:129]
	v_mfma_f32_16x16x32_f16 v[122:125], v[152:155], v[166:169], v[122:125]
	v_mfma_f32_16x16x32_f16 v[110:113], v[144:147], v[174:177], v[110:113]
	v_mfma_f32_16x16x32_f16 v[106:109], v[152:155], v[174:177], v[106:109]
	v_mfma_f32_16x16x32_f16 v[94:97], v[144:147], v[182:185], v[94:97]
	v_mfma_f32_16x16x32_f16 v[90:93], v[152:155], v[182:185], v[90:93]
	v_mfma_f32_16x16x32_f16 v[78:81], v[144:147], v[190:193], v[78:81]
	v_mfma_f32_16x16x32_f16 v[74:77], v[152:155], v[190:193], v[74:77]
	v_mfma_f32_16x16x32_f16 v[126:129], v[148:151], v[170:173], v[126:129]
	v_mfma_f32_16x16x32_f16 v[122:125], v[162:165], v[170:173], v[122:125]
	v_mfma_f32_16x16x32_f16 v[110:113], v[148:151], v[178:181], v[110:113]
	v_mfma_f32_16x16x32_f16 v[106:109], v[162:165], v[178:181], v[106:109]
	v_mfma_f32_16x16x32_f16 v[94:97], v[148:151], v[186:189], v[94:97]
	v_mfma_f32_16x16x32_f16 v[90:93], v[162:165], v[186:189], v[90:93]
	v_mfma_f32_16x16x32_f16 v[78:81], v[148:151], v[194:197], v[78:81]
	v_mfma_f32_16x16x32_f16 v[74:77], v[162:165], v[194:197], v[74:77]
	s_setprio 0
	s_barrier
	s_add_i32 s86, 0, 0x14000
	s_add_i32 s17, s17, s71
	v_add_u32_e32 v16, s86, v159
	v_lshl_add_u64 v[156:157], s[10:11], 0, v[136:137]
	s_mov_b32 m0, s17
	ds_read_b128 v[198:201], v16
	ds_read_b128 v[230:233], v16 offset:1024
	ds_read_b128 v[234:237], v16 offset:2048
	ds_read_b128 v[238:241], v16 offset:3072
	global_load_lds_dwordx4 v[156:157], off
	v_lshl_add_u64 v[242:243], s[10:11], 0, v[132:133]
	s_add_i32 m0, s17, 0x2000
	s_nop 0
	global_load_lds_dwordx4 v[242:243], off
	s_barrier
	s_waitcnt lgkmcnt(0)
	s_setprio 1
	s_waitcnt lgkmcnt(0)
	v_mfma_f32_16x16x32_f16 v[118:121], v[198:201], v[166:169], v[118:121]
	v_mfma_f32_16x16x32_f16 v[114:117], v[234:237], v[166:169], v[114:117]
	v_mfma_f32_16x16x32_f16 v[102:105], v[198:201], v[174:177], v[102:105]
	v_mfma_f32_16x16x32_f16 v[98:101], v[234:237], v[174:177], v[98:101]
	v_mfma_f32_16x16x32_f16 v[86:89], v[198:201], v[182:185], v[86:89]
	v_mfma_f32_16x16x32_f16 v[82:85], v[234:237], v[182:185], v[82:85]
	v_mfma_f32_16x16x32_f16 v[70:73], v[198:201], v[190:193], v[70:73]
	v_mfma_f32_16x16x32_f16 v[66:69], v[234:237], v[190:193], v[66:69]
	v_mfma_f32_16x16x32_f16 v[118:121], v[230:233], v[170:173], v[118:121]
	v_mfma_f32_16x16x32_f16 v[114:117], v[238:241], v[170:173], v[114:117]
	v_mfma_f32_16x16x32_f16 v[102:105], v[230:233], v[178:181], v[102:105]
	v_mfma_f32_16x16x32_f16 v[98:101], v[238:241], v[178:181], v[98:101]
	v_mfma_f32_16x16x32_f16 v[86:89], v[230:233], v[186:189], v[86:89]
	v_mfma_f32_16x16x32_f16 v[82:85], v[238:241], v[186:189], v[82:85]
	v_mfma_f32_16x16x32_f16 v[70:73], v[230:233], v[194:197], v[70:73]
	v_mfma_f32_16x16x32_f16 v[66:69], v[238:241], v[194:197], v[66:69]
	s_setprio 0
	s_mov_b32 m0, s82
	v_lshl_add_u64 v[244:245], s[8:9], 0, v[134:135]
	s_barrier
	ds_read_b128 v[166:169], v161 offset:16384
	ds_read_b128 v[170:173], v161 offset:17408
	ds_read_b128 v[174:177], v161 offset:18432
	ds_read_b128 v[178:181], v161 offset:19456
	ds_read_b128 v[182:185], v161 offset:20480
	ds_read_b128 v[186:189], v161 offset:21504
	ds_read_b128 v[190:193], v161 offset:22528
	ds_read_b128 v[194:197], v161 offset:23552
	global_load_lds_dwordx4 v[244:245], off
	v_lshl_add_u64 v[246:247], s[8:9], 0, v[130:131]
	s_mov_b32 m0, s83
	s_nop 0
	global_load_lds_dwordx4 v[246:247], off
	s_barrier
	s_waitcnt lgkmcnt(0)
	s_setprio 1
	s_waitcnt lgkmcnt(0)
	v_mfma_f32_16x16x32_f16 v[62:65], v[144:147], v[166:169], v[62:65]
	v_mfma_f32_16x16x32_f16 v[58:61], v[152:155], v[166:169], v[58:61]
	v_mfma_f32_16x16x32_f16 v[46:49], v[144:147], v[174:177], v[46:49]
	v_mfma_f32_16x16x32_f16 v[42:45], v[152:155], v[174:177], v[42:45]
	v_mfma_f32_16x16x32_f16 v[30:33], v[144:147], v[182:185], v[30:33]
	v_mfma_f32_16x16x32_f16 v[26:29], v[152:155], v[182:185], v[26:29]
	v_mfma_f32_16x16x32_f16 v[12:15], v[144:147], v[190:193], v[12:15]
	v_mfma_f32_16x16x32_f16 v[8:11], v[152:155], v[190:193], v[8:11]
	v_mfma_f32_16x16x32_f16 v[62:65], v[148:151], v[170:173], v[62:65]
	v_mfma_f32_16x16x32_f16 v[58:61], v[162:165], v[170:173], v[58:61]
	v_mfma_f32_16x16x32_f16 v[46:49], v[148:151], v[178:181], v[46:49]
	v_mfma_f32_16x16x32_f16 v[42:45], v[162:165], v[178:181], v[42:45]
	v_mfma_f32_16x16x32_f16 v[30:33], v[148:151], v[186:189], v[30:33]
	v_mfma_f32_16x16x32_f16 v[26:29], v[162:165], v[186:189], v[26:29]
	v_mfma_f32_16x16x32_f16 v[12:15], v[148:151], v[194:197], v[12:15]
	v_mfma_f32_16x16x32_f16 v[8:11], v[162:165], v[194:197], v[8:11]
	s_setprio 0
	s_barrier
; #define PG8_STAGE(bufoff, gbase, voff) do { _Pragma("unroll") for (int _i = 0; _i < 2; ++_i) \
;         __builtin_amdgcn_global_load_lds((const unsigned*)((const char*)(gbase) + (voff)[_i]), (LAS unsigned*)(lds + (bufoff) + ldsw + _i * 8192), 16, 0, 0); } while (0)
; #define PG8_LDA(dst, b, h) do { _Pragma("unroll") for (int m = 0; m < 4; ++m) _Pragma("unroll") for (int k = 0; k < 2; ++k) dst[m][k] = *(const LAS f16x8*)(lds + PG8_SA(b, h) + aoff + m * 2048 + k * 1024); } while (0)
; #define PG8_LDB(dst, b, h) do { _Pragma("unroll") for (int n = 0; n < 2; ++n) _Pragma("unroll") for (int k = 0; k < 2; ++k) dst[n][k] = *(const LAS f16x8*)(lds + PG8_SB(b, h) + boff + n * 2048 + k * 1024); } while (0)
; #define PG8_MMA(ai, bj, At, Bt) do { __builtin_amdgcn_s_setprio(1); _Pragma("unroll") for (int m = 0; m < 4; ++m) _Pragma("unroll") for (int n = 0; n < 2; ++n) _Pragma("unroll") for (int k = 0; k < 2; ++k) \
;         acc[ai][bj][m][n] = __builtin_amdgcn_mfma_f32_16x16x32_f16(Bt[n][k], At[m][k], acc[ai][bj][m][n], 0, 0, 0); __builtin_amdgcn_s_setprio(0); } while (0)
; #define PG8_WAIT_V(n) asm volatile("s_waitcnt vmcnt(" #n ")" ::: "memory")
; #define PG8_WAIT_L(n) asm volatile("s_waitcnt lgkmcnt(" #n ")" ::: "memory")
; #define PG8_BAR __builtin_amdgcn_s_barrier()
; #define PG8_SCHED __builtin_amdgcn_sched_barrier(0)
; template <class Epi, class Sched>
; __device__ __forceinline__ void gemm_phase(LAS unsigned char* lds, const Gemm g, const Sched& S, const Epi& E) {
;     ...
;             PG8_BAR; PG8_WAIT_L(0); PG8_MMA(1, 0, At, B0); PG8_BAR; PG8_SCHED;
;             PG8_STAGE(PG8_SB(0, 1), b2 + hstep, voffB);
;             PG8_WAIT_V(6); PG8_BAR; PG8_MMA(1, 1, At, B1); PG8_BAR;
;             PG8_LDB(B0, 1, 0); PG8_SCHED; PG8_LDA(At, 1, 0); PG8_STAGE(PG8_SA(0, 1), a2 + hstep, voffA);
;             PG8_WAIT_L(8); PG8_BAR; PG8_WAIT_L(0); PG8_MMA(0, 0, At, B0); PG8_BAR; PG8_SCHED;
;             PG8_LDB(B1, 1, 1); PG8_STAGE(PG8_SB(1, 0), b3, voffB);
;             PG8_BAR; PG8_WAIT_L(0); PG8_MMA(0, 1, At, B1); PG8_BAR;
;             PG8_LDA(At, 1, 1); PG8_STAGE(PG8_SA(1, 0), a3, voffA);
	s_add_u32 s10, s10, s44
	s_addc_u32 s11, s11, 0
	s_add_i32 s17, s86, s71
	v_lshl_add_u64 v[248:249], s[10:11], 0, v[136:137]
	s_mov_b32 m0, s17
	v_lshl_add_u64 v[250:251], s[10:11], 0, v[132:133]
	global_load_lds_dwordx4 v[248:249], off
	s_add_i32 m0, s17, 0x2000
	s_nop 0
	global_load_lds_dwordx4 v[250:251], off
	s_waitcnt vmcnt(6)
	s_barrier
	s_setprio 1
	v_mfma_f32_16x16x32_f16 v[54:57], v[198:201], v[166:169], v[54:57]
	v_mfma_f32_16x16x32_f16 v[50:53], v[234:237], v[166:169], v[50:53]
	v_mfma_f32_16x16x32_f16 v[38:41], v[198:201], v[174:177], v[38:41]
	v_mfma_f32_16x16x32_f16 v[34:37], v[234:237], v[174:177], v[34:37]
	v_mfma_f32_16x16x32_f16 v[22:25], v[198:201], v[182:185], v[22:25]
	v_mfma_f32_16x16x32_f16 v[18:21], v[234:237], v[182:185], v[18:21]
	v_mfma_f32_16x16x32_f16 v[4:7], v[198:201], v[190:193], v[4:7]
	v_mfma_f32_16x16x32_f16 v[0:3], v[234:237], v[190:193], v[0:3]
	v_mfma_f32_16x16x32_f16 v[54:57], v[230:233], v[170:173], v[54:57]
	v_mfma_f32_16x16x32_f16 v[50:53], v[238:241], v[170:173], v[50:53]
	v_mfma_f32_16x16x32_f16 v[38:41], v[230:233], v[178:181], v[38:41]
	v_mfma_f32_16x16x32_f16 v[34:37], v[238:241], v[178:181], v[34:37]
	v_mfma_f32_16x16x32_f16 v[22:25], v[230:233], v[186:189], v[22:25]
	v_mfma_f32_16x16x32_f16 v[18:21], v[238:241], v[186:189], v[18:21]
	v_mfma_f32_16x16x32_f16 v[4:7], v[230:233], v[194:197], v[4:7]
	v_mfma_f32_16x16x32_f16 v[0:3], v[238:241], v[194:197], v[0:3]
	s_setprio 0
	s_add_i32 s10, 0, 0x18000
	v_add_u32_e32 v16, s10, v159
	s_barrier
	ds_read_b128 v[144:147], v16
	ds_read_b128 v[148:151], v16 offset:1024
	ds_read_b128 v[152:155], v16 offset:2048
	ds_read_b128 v[162:165], v16 offset:3072
	s_add_u32 s8, s8, s44
	s_addc_u32 s9, s9, 0
	s_mov_b32 m0, s84
	v_lshl_add_u64 v[198:199], s[8:9], 0, v[134:135]
	ds_read_b128 v[166:169], v161 offset:32768
	ds_read_b128 v[170:173], v161 offset:33792
	ds_read_b128 v[174:177], v161 offset:34816
	ds_read_b128 v[178:181], v161 offset:35840
	ds_read_b128 v[182:185], v161 offset:36864
	ds_read_b128 v[186:189], v161 offset:37888
	ds_read_b128 v[190:193], v161 offset:38912
	ds_read_b128 v[194:197], v161 offset:39936
	global_load_lds_dwordx4 v[198:199], off
	v_lshl_add_u64 v[198:199], s[8:9], 0, v[130:131]
	s_mov_b32 m0, s85
	s_nop 0
	global_load_lds_dwordx4 v[198:199], off
	s_waitcnt lgkmcnt(8)
	s_barrier
	s_waitcnt lgkmcnt(0)
	s_setprio 1
	s_waitcnt lgkmcnt(0)
	v_mfma_f32_16x16x32_f16 v[126:129], v[144:147], v[166:169], v[126:129]
	v_mfma_f32_16x16x32_f16 v[122:125], v[152:155], v[166:169], v[122:125]
	v_mfma_f32_16x16x32_f16 v[110:113], v[144:147], v[174:177], v[110:113]
	v_mfma_f32_16x16x32_f16 v[106:109], v[152:155], v[174:177], v[106:109]
	v_mfma_f32_16x16x32_f16 v[94:97], v[144:147], v[182:185], v[94:97]
	v_mfma_f32_16x16x32_f16 v[90:93], v[152:155], v[182:185], v[90:93]
	v_mfma_f32_16x16x32_f16 v[78:81], v[144:147], v[190:193], v[78:81]
	v_mfma_f32_16x16x32_f16 v[74:77], v[152:155], v[190:193], v[74:77]
	v_mfma_f32_16x16x32_f16 v[126:129], v[148:151], v[170:173], v[126:129]
	v_mfma_f32_16x16x32_f16 v[122:125], v[162:165], v[170:173], v[122:125]
	v_mfma_f32_16x16x32_f16 v[110:113], v[148:151], v[178:181], v[110:113]
	v_mfma_f32_16x16x32_f16 v[106:109], v[162:165], v[178:181], v[106:109]
	v_mfma_f32_16x16x32_f16 v[94:97], v[148:151], v[186:189], v[94:97]
	v_mfma_f32_16x16x32_f16 v[90:93], v[162:165], v[186:189], v[90:93]
	v_mfma_f32_16x16x32_f16 v[78:81], v[148:151], v[194:197], v[78:81]
	v_mfma_f32_16x16x32_f16 v[74:77], v[162:165], v[194:197], v[74:77]
	s_setprio 0
	s_barrier
	s_add_i32 s8, 0, 0x1c000
	s_add_i32 s9, s10, s71
	v_add_u32_e32 v16, s8, v159
	v_lshl_add_u64 v[156:157], v[156:157], 0, s[90:91]
	s_mov_b32 m0, s9
	ds_read_b128 v[198:201], v16
	ds_read_b128 v[230:233], v16 offset:1024
	ds_read_b128 v[234:237], v16 offset:2048
	ds_read_b128 v[238:241], v16 offset:3072
	global_load_lds_dwordx4 v[156:157], off
	v_lshl_add_u64 v[156:157], v[242:243], 0, s[90:91]
	s_add_i32 m0, s9, 0x2000
	s_nop 0
	global_load_lds_dwordx4 v[156:157], off
	s_barrier
	s_waitcnt lgkmcnt(0)
	s_setprio 1
	s_waitcnt lgkmcnt(0)
	v_mfma_f32_16x16x32_f16 v[118:121], v[198:201], v[166:169], v[118:121]
	v_mfma_f32_16x16x32_f16 v[114:117], v[234:237], v[166:169], v[114:117]
	v_mfma_f32_16x16x32_f16 v[102:105], v[198:201], v[174:177], v[102:105]
	v_mfma_f32_16x16x32_f16 v[98:101], v[234:237], v[174:177], v[98:101]
	v_mfma_f32_16x16x32_f16 v[86:89], v[198:201], v[182:185], v[86:89]
	v_mfma_f32_16x16x32_f16 v[82:85], v[234:237], v[182:185], v[82:85]
	v_mfma_f32_16x16x32_f16 v[70:73], v[198:201], v[190:193], v[70:73]
	v_mfma_f32_16x16x32_f16 v[66:69], v[234:237], v[190:193], v[66:69]
	v_mfma_f32_16x16x32_f16 v[118:121], v[230:233], v[170:173], v[118:121]
	v_mfma_f32_16x16x32_f16 v[114:117], v[238:241], v[170:173], v[114:117]
	v_mfma_f32_16x16x32_f16 v[102:105], v[230:233], v[178:181], v[102:105]
	v_mfma_f32_16x16x32_f16 v[98:101], v[238:241], v[178:181], v[98:101]
	v_mfma_f32_16x16x32_f16 v[86:89], v[230:233], v[186:189], v[86:89]
	v_mfma_f32_16x16x32_f16 v[82:85], v[238:241], v[186:189], v[82:85]
	v_mfma_f32_16x16x32_f16 v[70:73], v[230:233], v[194:197], v[70:73]
	v_mfma_f32_16x16x32_f16 v[66:69], v[238:241], v[194:197], v[66:69]
	s_setprio 0
	s_mov_b32 m0, s94
	v_lshl_add_u64 v[156:157], v[244:245], 0, s[90:91]
	s_barrier
	ds_read_b128 v[166:169], v161 offset:49152
	ds_read_b128 v[170:173], v161 offset:50176
	ds_read_b128 v[174:177], v161 offset:51200
	ds_read_b128 v[178:181], v161 offset:52224
	ds_read_b128 v[182:185], v161 offset:53248
	ds_read_b128 v[186:189], v161 offset:54272
	ds_read_b128 v[190:193], v161 offset:55296
	ds_read_b128 v[194:197], v161 offset:56320
	global_load_lds_dwordx4 v[156:157], off
	v_lshl_add_u64 v[156:157], v[246:247], 0, s[90:91]
	s_mov_b32 m0, s95
	s_nop 0
	global_load_lds_dwordx4 v[156:157], off
	s_barrier
; #define PG8_STAGE(bufoff, gbase, voff) do { _Pragma("unroll") for (int _i = 0; _i < 2; ++_i) \
;         __builtin_amdgcn_global_load_lds((const unsigned*)((const char*)(gbase) + (voff)[_i]), (LAS unsigned*)(lds + (bufoff) + ldsw + _i * 8192), 16, 0, 0); } while (0)
; #define PG8_LDA(dst, b, h) do { _Pragma("unroll") for (int m = 0; m < 4; ++m) _Pragma("unroll") for (int k = 0; k < 2; ++k) dst[m][k] = *(const LAS f16x8*)(lds + PG8_SA(b, h) + aoff + m * 2048 + k * 1024); } while (0)
; #define PG8_MMA(ai, bj, At, Bt) do { __builtin_amdgcn_s_setprio(1); _Pragma("unroll") for (int m = 0; m < 4; ++m) _Pragma("unroll") for (int n = 0; n < 2; ++n) _Pragma("unroll") for (int k = 0; k < 2; ++k) \
;         acc[ai][bj][m][n] = __builtin_amdgcn_mfma_f32_16x16x32_f16(Bt[n][k], At[m][k], acc[ai][bj][m][n], 0, 0, 0); __builtin_amdgcn_s_setprio(0); } while (0)
;     __device__ __forceinline__ void operator()(const f32x4 (&acc)[2][2][4][2], const Unit& u, int wr, int wc, int fr, int fq) const {
;     ...
;             const int row0 = u.pm * BM + wr * 64 + fr; const int col0 = u.pn * BM + wc * 32 + 8 * fq;
;             const float lo = mode == 1 ? 0.f : -3.0e38f;
; #pragma unroll
;             for (int ai = 0; ai < 2; ++ai)
; #pragma unroll
;                 for (int m = 0; m < 4; ++m) { f16_t* rowp = O + (size_t)(row0 + ai * HALF + m * 16) * ldc + col0;
; #pragma unroll
;                     for (int bj = 0; bj < 2; ++bj) { f32x4 v0 = acc[ai][bj][m][0], v1 = acc[ai][bj][m][1];
;                         if (mode == 1) {
; #pragma unroll
;                             for (int j = 0; j < 4; ++j) { float a = fmaxf(v0[j], lo), b = fmaxf(v1[j], lo); v0[j] = a * a; v1[j] = b * b; } }
;                         u32x4 w; w.x = pkh(v0[0], v0[1]); w.y = pkh(v0[2], v0[3]); w.z = pkh(v1[0], v1[1]); w.w = pkh(v1[2], v1[3]);
;                         *(u32x4*)(rowp + bj * HALF) = w; } }
; template <class Epi, class Sched>
; __device__ __forceinline__ void gemm_phase(LAS unsigned char* lds, const Gemm g, const Sched& S, const Epi& E) {
;     ...
;             PG8_LDA(At, 1, 1); PG8_STAGE(PG8_SA(1, 0), a3, voffA);
;             PG8_BAR; PG8_WAIT_L(0); PG8_MMA(1, 0, At, B0); PG8_BAR; PG8_SCHED;
;             PG8_STAGE(PG8_SB(1, 1), b3 + hstep, voffB);
;             PG8_WAIT_V(6); PG8_BAR; PG8_MMA(1, 1, At, B1); PG8_BAR;
;         }
;         E(acc, cur, wr, wc, fr, fq); S.done(cur);
	s_waitcnt lgkmcnt(0)
	s_setprio 1
	s_waitcnt lgkmcnt(0)
	v_mfma_f32_16x16x32_f16 v[62:65], v[144:147], v[166:169], v[62:65]
	v_mfma_f32_16x16x32_f16 v[58:61], v[152:155], v[166:169], v[58:61]
	v_mfma_f32_16x16x32_f16 v[46:49], v[144:147], v[174:177], v[46:49]
	v_mfma_f32_16x16x32_f16 v[42:45], v[152:155], v[174:177], v[42:45]
	v_mfma_f32_16x16x32_f16 v[30:33], v[144:147], v[182:185], v[30:33]
	v_mfma_f32_16x16x32_f16 v[26:29], v[152:155], v[182:185], v[26:29]
	v_mfma_f32_16x16x32_f16 v[12:15], v[144:147], v[190:193], v[12:15]
	v_mfma_f32_16x16x32_f16 v[8:11], v[152:155], v[190:193], v[8:11]
	v_mfma_f32_16x16x32_f16 v[62:65], v[148:151], v[170:173], v[62:65]
	v_mfma_f32_16x16x32_f16 v[58:61], v[162:165], v[170:173], v[58:61]
	v_mfma_f32_16x16x32_f16 v[46:49], v[148:151], v[178:181], v[46:49]
	v_mfma_f32_16x16x32_f16 v[42:45], v[162:165], v[178:181], v[42:45]
	v_mfma_f32_16x16x32_f16 v[30:33], v[148:151], v[186:189], v[30:33]
	v_mfma_f32_16x16x32_f16 v[26:29], v[162:165], v[186:189], v[26:29]
	v_mfma_f32_16x16x32_f16 v[12:15], v[148:151], v[194:197], v[12:15]
	v_mfma_f32_16x16x32_f16 v[8:11], v[162:165], v[194:197], v[8:11]
	s_setprio 0
	s_barrier
	s_add_i32 s8, s8, s71
	v_lshl_add_u64 v[144:145], v[248:249], 0, s[90:91]
	s_mov_b32 m0, s8
	s_nop 0
	global_load_lds_dwordx4 v[144:145], off
	v_lshl_add_u64 v[144:145], v[250:251], 0, s[90:91]
	s_add_i32 m0, s8, 0x2000
	s_nop 0
	global_load_lds_dwordx4 v[144:145], off
	s_waitcnt vmcnt(6)
	s_barrier
	s_setprio 1
	v_mfma_f32_16x16x32_f16 v[54:57], v[198:201], v[166:169], v[54:57]
	v_mfma_f32_16x16x32_f16 v[50:53], v[234:237], v[166:169], v[50:53]
	v_mfma_f32_16x16x32_f16 v[38:41], v[198:201], v[174:177], v[38:41]
	v_mfma_f32_16x16x32_f16 v[34:37], v[234:237], v[174:177], v[34:37]
	v_mfma_f32_16x16x32_f16 v[22:25], v[198:201], v[182:185], v[22:25]
	v_mfma_f32_16x16x32_f16 v[18:21], v[234:237], v[182:185], v[18:21]
	v_mfma_f32_16x16x32_f16 v[4:7], v[198:201], v[190:193], v[4:7]
	v_mfma_f32_16x16x32_f16 v[0:3], v[234:237], v[190:193], v[0:3]
	v_mfma_f32_16x16x32_f16 v[54:57], v[230:233], v[170:173], v[54:57]
	v_mfma_f32_16x16x32_f16 v[50:53], v[238:241], v[170:173], v[50:53]
	v_mfma_f32_16x16x32_f16 v[38:41], v[230:233], v[178:181], v[38:41]
	v_mfma_f32_16x16x32_f16 v[34:37], v[238:241], v[178:181], v[34:37]
	v_mfma_f32_16x16x32_f16 v[22:25], v[230:233], v[186:189], v[22:25]
	v_mfma_f32_16x16x32_f16 v[18:21], v[238:241], v[186:189], v[18:21]
	v_mfma_f32_16x16x32_f16 v[4:7], v[230:233], v[194:197], v[4:7]
	v_mfma_f32_16x16x32_f16 v[0:3], v[238:241], v[194:197], v[0:3]
	s_setprio 0
	s_add_u32 s6, s6, 0x100
	s_addc_u32 s7, s7, 0
	s_add_u32 s41, s41, 0x100
	s_addc_u32 vcc_lo, vcc_lo, 0
	s_cmp_ge_u32 vcc_hi, s77
	s_mov_b32 s8, vcc_hi
	s_barrier
	s_cbranch_scc0 .LBB0_829
	v_lshl_add_u32 v162, s36, 8, v139
	v_ashrrev_i32_e32 v16, 31, v162
	s_lshl_b32 s3, s3, 8
	v_mul_lo_u32 v163, s54, v16
	v_mul_lo_u32 v16, s55, v162
	v_mad_u64_u32 v[144:145], s[6:7], s54, v162, 0
	s_or_b32 s3, s3, s89
	v_add3_u32 v145, v145, v163, v16
	s_mov_b64 s[6:7], -1
	s_and_b64 vcc, exec, s[42:43]
	s_movk_i32 s86, 0x41ff
	s_cbranch_vccz .LBB0_864
	v_cndmask_b32_e64 v16, 0, 1, s[48:49]
	v_cmp_ne_u32_e64 s[40:41], 1, v16
	s_andn2_b64 vcc, exec, s[48:49]
	v_or_b32_e32 v16, s3, v158
	v_lshlrev_b32_e32 v16, 1, v16
	v_lshl_add_u64 v[146:147], s[52:53], 0, v[16:17]
	v_lshl_add_u64 v[148:149], v[144:145], 1, v[146:147]
	s_cbranch_vccnz .Lep0_0
	v_max_f32_e32 v150, 0, v126
	v_max_f32_e32 v151, 0, v127
	v_max_f32_e32 v152, 0, v128
	v_max_f32_e32 v153, 0, v129
	v_max_f32_e32 v154, 0, v122
	v_max_f32_e32 v155, 0, v123
	v_max_f32_e32 v156, 0, v124
	v_max_f32_e32 v157, 0, v125
	v_pk_mul_f32 v[150:151], v[150:151], v[150:151]
	v_pk_mul_f32 v[152:153], v[152:153], v[152:153]
	v_pk_mul_f32 v[154:155], v[154:155], v[154:155]
	v_pk_mul_f32 v[156:157], v[156:157], v[156:157]
	v_cvt_pk_f16_f32 v150, v150, v151
	v_cvt_pk_f16_f32 v151, v152, v153
	v_cvt_pk_f16_f32 v152, v154, v155
	v_cvt_pk_f16_f32 v153, v156, v157
	s_branch .Lep1_0
.Lep0_0:
	v_cvt_pk_f16_f32 v150, v126, v127
	v_cvt_pk_f16_f32 v151, v128, v129
	v_cvt_pk_f16_f32 v152, v122, v123
	v_cvt_pk_f16_f32 v153, v124, v125
.Lep1_0:
	global_store_dwordx4 v[148:149], v[150:153], off
	s_and_b64 vcc, exec, s[40:41]
	s_cbranch_vccnz .Lep0_1
	v_max_f32_e32 v150, 0, v118
	v_max_f32_e32 v151, 0, v119
	v_max_f32_e32 v152, 0, v120
	v_max_f32_e32 v153, 0, v121
	v_max_f32_e32 v154, 0, v114
	v_max_f32_e32 v155, 0, v115
	v_max_f32_e32 v156, 0, v116
	v_max_f32_e32 v157, 0, v117
	v_pk_mul_f32 v[150:151], v[150:151], v[150:151]
	v_pk_mul_f32 v[152:153], v[152:153], v[152:153]
	v_pk_mul_f32 v[154:155], v[154:155], v[154:155]
	v_pk_mul_f32 v[156:157], v[156:157], v[156:157]
	v_cvt_pk_f16_f32 v150, v150, v151
	v_cvt_pk_f16_f32 v151, v152, v153
	v_cvt_pk_f16_f32 v152, v154, v155
	v_cvt_pk_f16_f32 v153, v156, v157
	s_branch .Lep1_1
.Lep0_1:
	v_cvt_pk_f16_f32 v150, v118, v119
	v_cvt_pk_f16_f32 v151, v120, v121
	v_cvt_pk_f16_f32 v152, v114, v115
	v_cvt_pk_f16_f32 v153, v116, v117
.Lep1_1:
	global_store_dwordx4 v[148:149], v[150:153], off offset:256
	s_and_b64 vcc, exec, s[40:41]
	v_or_b32_e32 v16, 16, v162
	v_mul_lo_u32 v164, s55, v16
	v_mad_u64_u32 v[148:149], s[6:7], s54, v16, 0
	v_add3_u32 v149, v149, v163, v164
	v_lshl_add_u64 v[148:149], v[148:149], 1, v[146:147]
	s_cbranch_vccnz .Lep0_2
	v_max_f32_e32 v150, 0, v110
	v_max_f32_e32 v151, 0, v111
	v_max_f32_e32 v152, 0, v112
	v_max_f32_e32 v153, 0, v113
	v_max_f32_e32 v154, 0, v106
	v_max_f32_e32 v155, 0, v107
	v_max_f32_e32 v156, 0, v108
	v_max_f32_e32 v157, 0, v109
	v_pk_mul_f32 v[150:151], v[150:151], v[150:151]
	v_pk_mul_f32 v[152:153], v[152:153], v[152:153]
	v_pk_mul_f32 v[154:155], v[154:155], v[154:155]
	v_pk_mul_f32 v[156:157], v[156:157], v[156:157]
	v_cvt_pk_f16_f32 v150, v150, v151
	v_cvt_pk_f16_f32 v151, v152, v153
	v_cvt_pk_f16_f32 v152, v154, v155
	v_cvt_pk_f16_f32 v153, v156, v157
	s_branch .Lep1_2
;     __device__ __forceinline__ void operator()(const f32x4 (&acc)[2][2][4][2], const Unit& u, int wr, int wc, int fr, int fq) const {
;     ...
;             for (int ai = 0; ai < 2; ++ai)
; #pragma unroll
;                 for (int m = 0; m < 4; ++m) { f16_t* rowp = O + (size_t)(row0 + ai * HALF + m * 16) * ldc + col0;
; #pragma unroll
;                     for (int bj = 0; bj < 2; ++bj) { f32x4 v0 = acc[ai][bj][m][0], v1 = acc[ai][bj][m][1];
;                         if (mode == 1) {
; #pragma unroll
;                             for (int j = 0; j < 4; ++j) { float a = fmaxf(v0[j], lo), b = fmaxf(v1[j], lo); v0[j] = a * a; v1[j] = b * b; } }
;                         u32x4 w; w.x = pkh(v0[0], v0[1]); w.y = pkh(v0[2], v0[3]); w.z = pkh(v1[0], v1[1]); w.w = pkh(v1[2], v1[3]);
;                         *(u32x4*)(rowp + bj * HALF) = w; } }
.Lep0_2:
	v_cvt_pk_f16_f32 v150, v110, v111
	v_cvt_pk_f16_f32 v151, v112, v113
	v_cvt_pk_f16_f32 v152, v106, v107
	v_cvt_pk_f16_f32 v153, v108, v109
.Lep1_2:
	global_store_dwordx4 v[148:149], v[150:153], off
	s_and_b64 vcc, exec, s[40:41]
	s_cbranch_vccnz .Lep0_3
	v_max_f32_e32 v150, 0, v102
	v_max_f32_e32 v151, 0, v103
	v_max_f32_e32 v152, 0, v104
	v_max_f32_e32 v153, 0, v105
	v_max_f32_e32 v154, 0, v98
	v_max_f32_e32 v155, 0, v99
	v_max_f32_e32 v156, 0, v100
	v_max_f32_e32 v157, 0, v101
	v_pk_mul_f32 v[150:151], v[150:151], v[150:151]
	v_pk_mul_f32 v[152:153], v[152:153], v[152:153]
	v_pk_mul_f32 v[154:155], v[154:155], v[154:155]
	v_pk_mul_f32 v[156:157], v[156:157], v[156:157]
	v_cvt_pk_f16_f32 v150, v150, v151
	v_cvt_pk_f16_f32 v151, v152, v153
	v_cvt_pk_f16_f32 v152, v154, v155
	v_cvt_pk_f16_f32 v153, v156, v157
	s_branch .Lep1_3
.Lep0_3:
	v_cvt_pk_f16_f32 v150, v102, v103
	v_cvt_pk_f16_f32 v151, v104, v105
	v_cvt_pk_f16_f32 v152, v98, v99
	v_cvt_pk_f16_f32 v153, v100, v101
.Lep1_3:
	global_store_dwordx4 v[148:149], v[150:153], off offset:256
	s_and_b64 vcc, exec, s[40:41]
	v_or_b32_e32 v16, 32, v162
	v_mul_lo_u32 v164, s55, v16
	v_mad_u64_u32 v[148:149], s[6:7], s54, v16, 0
	v_add3_u32 v149, v149, v163, v164
	v_lshl_add_u64 v[148:149], v[148:149], 1, v[146:147]
	s_cbranch_vccnz .Lep0_4
	v_max_f32_e32 v150, 0, v94
	v_max_f32_e32 v151, 0, v95
	v_max_f32_e32 v152, 0, v96
	v_max_f32_e32 v153, 0, v97
	v_max_f32_e32 v154, 0, v90
	v_max_f32_e32 v155, 0, v91
	v_max_f32_e32 v156, 0, v92
	v_max_f32_e32 v157, 0, v93
	v_pk_mul_f32 v[150:151], v[150:151], v[150:151]
	v_pk_mul_f32 v[152:153], v[152:153], v[152:153]
	v_pk_mul_f32 v[154:155], v[154:155], v[154:155]
	v_pk_mul_f32 v[156:157], v[156:157], v[156:157]
	v_cvt_pk_f16_f32 v150, v150, v151
	v_cvt_pk_f16_f32 v151, v152, v153
	v_cvt_pk_f16_f32 v152, v154, v155
	v_cvt_pk_f16_f32 v153, v156, v157
	s_branch .Lep1_4
.Lep0_4:
	v_cvt_pk_f16_f32 v150, v94, v95
	v_cvt_pk_f16_f32 v151, v96, v97
	v_cvt_pk_f16_f32 v152, v90, v91
	v_cvt_pk_f16_f32 v153, v92, v93
.Lep1_4:
	global_store_dwordx4 v[148:149], v[150:153], off
	s_and_b64 vcc, exec, s[40:41]
	s_cbranch_vccnz .Lep0_5
	v_max_f32_e32 v150, 0, v86
	v_max_f32_e32 v151, 0, v87
	v_max_f32_e32 v152, 0, v88
	v_max_f32_e32 v153, 0, v89
	v_max_f32_e32 v154, 0, v82
	v_max_f32_e32 v155, 0, v83
	v_max_f32_e32 v156, 0, v84
	v_max_f32_e32 v157, 0, v85
	v_pk_mul_f32 v[150:151], v[150:151], v[150:151]
	v_pk_mul_f32 v[152:153], v[152:153], v[152:153]
	v_pk_mul_f32 v[154:155], v[154:155], v[154:155]
	v_pk_mul_f32 v[156:157], v[156:157], v[156:157]
	v_cvt_pk_f16_f32 v150, v150, v151
	v_cvt_pk_f16_f32 v151, v152, v153
	v_cvt_pk_f16_f32 v152, v154, v155
	v_cvt_pk_f16_f32 v153, v156, v157
	s_branch .Lep1_5
.Lep0_5:
	v_cvt_pk_f16_f32 v150, v86, v87
	v_cvt_pk_f16_f32 v151, v88, v89
	v_cvt_pk_f16_f32 v152, v82, v83
	v_cvt_pk_f16_f32 v153, v84, v85
.Lep1_5:
	global_store_dwordx4 v[148:149], v[150:153], off offset:256
	s_and_b64 vcc, exec, s[40:41]
	v_or_b32_e32 v16, 48, v162
	v_mul_lo_u32 v164, s55, v16
	v_mad_u64_u32 v[148:149], s[6:7], s54, v16, 0
	v_add3_u32 v149, v149, v163, v164
	v_lshl_add_u64 v[148:149], v[148:149], 1, v[146:147]
	s_cbranch_vccnz .Lep0_6
	v_max_f32_e32 v150, 0, v78
	v_max_f32_e32 v151, 0, v79
	v_max_f32_e32 v152, 0, v80
	v_max_f32_e32 v153, 0, v81
	v_max_f32_e32 v154, 0, v74
	v_max_f32_e32 v155, 0, v75
	v_max_f32_e32 v156, 0, v76
	v_max_f32_e32 v157, 0, v77
	v_pk_mul_f32 v[150:151], v[150:151], v[150:151]
	v_pk_mul_f32 v[152:153], v[152:153], v[152:153]
	v_pk_mul_f32 v[154:155], v[154:155], v[154:155]
	v_pk_mul_f32 v[156:157], v[156:157], v[156:157]
	v_cvt_pk_f16_f32 v150, v150, v151
	v_cvt_pk_f16_f32 v151, v152, v153
	v_cvt_pk_f16_f32 v152, v154, v155
	v_cvt_pk_f16_f32 v153, v156, v157
	s_branch .Lep1_6
.Lep0_6:
	v_cvt_pk_f16_f32 v150, v78, v79
	v_cvt_pk_f16_f32 v151, v80, v81
	v_cvt_pk_f16_f32 v152, v74, v75
	v_cvt_pk_f16_f32 v153, v76, v77
.Lep1_6:
	global_store_dwordx4 v[148:149], v[150:153], off
	s_and_b64 vcc, exec, s[40:41]
	s_cbranch_vccnz .Lep0_7
	v_max_f32_e32 v150, 0, v70
	v_max_f32_e32 v151, 0, v71
	v_max_f32_e32 v152, 0, v72
	v_max_f32_e32 v153, 0, v73
	v_max_f32_e32 v154, 0, v66
	v_max_f32_e32 v155, 0, v67
	v_max_f32_e32 v156, 0, v68
	v_max_f32_e32 v157, 0, v69
	v_pk_mul_f32 v[150:151], v[150:151], v[150:151]
	v_pk_mul_f32 v[152:153], v[152:153], v[152:153]
	v_pk_mul_f32 v[154:155], v[154:155], v[154:155]
	v_pk_mul_f32 v[156:157], v[156:157], v[156:157]
	v_cvt_pk_f16_f32 v150, v150, v151
	v_cvt_pk_f16_f32 v151, v152, v153
	v_cvt_pk_f16_f32 v152, v154, v155
	v_cvt_pk_f16_f32 v153, v156, v157
	s_branch .Lep1_7
.Lep0_7:
	v_cvt_pk_f16_f32 v150, v70, v71
	v_cvt_pk_f16_f32 v151, v72, v73
	v_cvt_pk_f16_f32 v152, v66, v67
	v_cvt_pk_f16_f32 v153, v68, v69
.Lep1_7:
	global_store_dwordx4 v[148:149], v[150:153], off offset:256
	s_and_b64 vcc, exec, s[40:41]
	v_add_u32_e32 v16, 0x80, v162
	v_ashrrev_i32_e32 v148, 31, v16
	v_mul_lo_u32 v164, s54, v148
	v_mul_lo_u32 v165, s55, v16
	v_mad_u64_u32 v[148:149], s[6:7], s54, v16, 0
	v_add3_u32 v149, v149, v164, v165
	v_lshl_add_u64 v[148:149], v[148:149], 1, v[146:147]
	s_cbranch_vccnz .Lep0_8
	v_max_f32_e32 v150, 0, v62
	v_max_f32_e32 v151, 0, v63
	v_max_f32_e32 v152, 0, v64
	v_max_f32_e32 v153, 0, v65
	v_max_f32_e32 v154, 0, v58
	v_max_f32_e32 v155, 0, v59
	v_max_f32_e32 v156, 0, v60
	v_max_f32_e32 v157, 0, v61
	v_pk_mul_f32 v[150:151], v[150:151], v[150:151]
	v_pk_mul_f32 v[152:153], v[152:153], v[152:153]
	v_pk_mul_f32 v[154:155], v[154:155], v[154:155]
	v_pk_mul_f32 v[156:157], v[156:157], v[156:157]
	v_cvt_pk_f16_f32 v150, v150, v151
	v_cvt_pk_f16_f32 v151, v152, v153
	v_cvt_pk_f16_f32 v152, v154, v155
	v_cvt_pk_f16_f32 v153, v156, v157
	s_branch .Lep1_8
;     __device__ __forceinline__ void operator()(const f32x4 (&acc)[2][2][4][2], const Unit& u, int wr, int wc, int fr, int fq) const {
;     ...
;             for (int ai = 0; ai < 2; ++ai)
; #pragma unroll
;                 for (int m = 0; m < 4; ++m) { f16_t* rowp = O + (size_t)(row0 + ai * HALF + m * 16) * ldc + col0;
; #pragma unroll
;                     for (int bj = 0; bj < 2; ++bj) { f32x4 v0 = acc[ai][bj][m][0], v1 = acc[ai][bj][m][1];
;                         if (mode == 1) {
; #pragma unroll
;                             for (int j = 0; j < 4; ++j) { float a = fmaxf(v0[j], lo), b = fmaxf(v1[j], lo); v0[j] = a * a; v1[j] = b * b; } }
;                         u32x4 w; w.x = pkh(v0[0], v0[1]); w.y = pkh(v0[2], v0[3]); w.z = pkh(v1[0], v1[1]); w.w = pkh(v1[2], v1[3]);
;                         *(u32x4*)(rowp + bj * HALF) = w; } }
.Lep0_8:
	v_cvt_pk_f16_f32 v150, v62, v63
	v_cvt_pk_f16_f32 v151, v64, v65
	v_cvt_pk_f16_f32 v152, v58, v59
	v_cvt_pk_f16_f32 v153, v60, v61
.Lep1_8:
	global_store_dwordx4 v[148:149], v[150:153], off
	s_and_b64 vcc, exec, s[40:41]
	s_cbranch_vccnz .Lep0_9
	v_max_f32_e32 v150, 0, v54
	v_max_f32_e32 v151, 0, v55
	v_max_f32_e32 v152, 0, v56
	v_max_f32_e32 v153, 0, v57
	v_max_f32_e32 v154, 0, v50
	v_max_f32_e32 v155, 0, v51
	v_max_f32_e32 v156, 0, v52
	v_max_f32_e32 v157, 0, v53
	v_pk_mul_f32 v[150:151], v[150:151], v[150:151]
	v_pk_mul_f32 v[152:153], v[152:153], v[152:153]
	v_pk_mul_f32 v[154:155], v[154:155], v[154:155]
	v_pk_mul_f32 v[156:157], v[156:157], v[156:157]
	v_cvt_pk_f16_f32 v150, v150, v151
	v_cvt_pk_f16_f32 v151, v152, v153
	v_cvt_pk_f16_f32 v152, v154, v155
	v_cvt_pk_f16_f32 v153, v156, v157
	s_branch .Lep1_9
.Lep0_9:
	v_cvt_pk_f16_f32 v150, v54, v55
	v_cvt_pk_f16_f32 v151, v56, v57
	v_cvt_pk_f16_f32 v152, v50, v51
	v_cvt_pk_f16_f32 v153, v52, v53
.Lep1_9:
	global_store_dwordx4 v[148:149], v[150:153], off offset:256
	s_and_b64 vcc, exec, s[40:41]
	v_add_u32_e32 v16, 0x90, v162
	v_ashrrev_i32_e32 v148, 31, v16
	v_mul_lo_u32 v164, s54, v148
	v_mul_lo_u32 v165, s55, v16
	v_mad_u64_u32 v[148:149], s[6:7], s54, v16, 0
	v_add3_u32 v149, v149, v164, v165
	v_lshl_add_u64 v[148:149], v[148:149], 1, v[146:147]
	s_cbranch_vccnz .Lep0_10
	v_max_f32_e32 v150, 0, v46
	v_max_f32_e32 v151, 0, v47
	v_max_f32_e32 v152, 0, v48
	v_max_f32_e32 v153, 0, v49
	v_max_f32_e32 v154, 0, v42
	v_max_f32_e32 v155, 0, v43
	v_max_f32_e32 v156, 0, v44
	v_max_f32_e32 v157, 0, v45
	v_pk_mul_f32 v[150:151], v[150:151], v[150:151]
	v_pk_mul_f32 v[152:153], v[152:153], v[152:153]
	v_pk_mul_f32 v[154:155], v[154:155], v[154:155]
	v_pk_mul_f32 v[156:157], v[156:157], v[156:157]
	v_cvt_pk_f16_f32 v150, v150, v151
	v_cvt_pk_f16_f32 v151, v152, v153
	v_cvt_pk_f16_f32 v152, v154, v155
	v_cvt_pk_f16_f32 v153, v156, v157
	s_branch .Lep1_10
.Lep0_10:
	v_cvt_pk_f16_f32 v150, v46, v47
	v_cvt_pk_f16_f32 v151, v48, v49
	v_cvt_pk_f16_f32 v152, v42, v43
	v_cvt_pk_f16_f32 v153, v44, v45
.Lep1_10:
	global_store_dwordx4 v[148:149], v[150:153], off
	s_and_b64 vcc, exec, s[40:41]
	s_cbranch_vccnz .Lep0_11
	v_max_f32_e32 v150, 0, v38
	v_max_f32_e32 v151, 0, v39
	v_max_f32_e32 v152, 0, v40
	v_max_f32_e32 v153, 0, v41
	v_max_f32_e32 v154, 0, v34
	v_max_f32_e32 v155, 0, v35
	v_max_f32_e32 v156, 0, v36
	v_max_f32_e32 v157, 0, v37
	v_pk_mul_f32 v[150:151], v[150:151], v[150:151]
	v_pk_mul_f32 v[152:153], v[152:153], v[152:153]
	v_pk_mul_f32 v[154:155], v[154:155], v[154:155]
	v_pk_mul_f32 v[156:157], v[156:157], v[156:157]
	v_cvt_pk_f16_f32 v150, v150, v151
	v_cvt_pk_f16_f32 v151, v152, v153
	v_cvt_pk_f16_f32 v152, v154, v155
	v_cvt_pk_f16_f32 v153, v156, v157
	s_branch .Lep1_11
.Lep0_11:
	v_cvt_pk_f16_f32 v150, v38, v39
	v_cvt_pk_f16_f32 v151, v40, v41
	v_cvt_pk_f16_f32 v152, v34, v35
	v_cvt_pk_f16_f32 v153, v36, v37
.Lep1_11:
	global_store_dwordx4 v[148:149], v[150:153], off offset:256
	s_and_b64 vcc, exec, s[40:41]
	v_add_u32_e32 v16, 0xa0, v162
	v_ashrrev_i32_e32 v148, 31, v16
	v_mul_lo_u32 v164, s54, v148
	v_mul_lo_u32 v165, s55, v16
	v_mad_u64_u32 v[148:149], s[6:7], s54, v16, 0
	v_add3_u32 v149, v149, v164, v165
	v_lshl_add_u64 v[148:149], v[148:149], 1, v[146:147]
	s_cbranch_vccnz .Lep0_12
	v_max_f32_e32 v150, 0, v30
	v_max_f32_e32 v151, 0, v31
	v_max_f32_e32 v152, 0, v32
	v_max_f32_e32 v153, 0, v33
	v_max_f32_e32 v154, 0, v26
	v_max_f32_e32 v155, 0, v27
	v_max_f32_e32 v156, 0, v28
	v_max_f32_e32 v157, 0, v29
	v_pk_mul_f32 v[150:151], v[150:151], v[150:151]
	v_pk_mul_f32 v[152:153], v[152:153], v[152:153]
	v_pk_mul_f32 v[154:155], v[154:155], v[154:155]
	v_pk_mul_f32 v[156:157], v[156:157], v[156:157]
	v_cvt_pk_f16_f32 v150, v150, v151
	v_cvt_pk_f16_f32 v151, v152, v153
	v_cvt_pk_f16_f32 v152, v154, v155
	v_cvt_pk_f16_f32 v153, v156, v157
	s_branch .Lep1_12
.Lep0_12:
	v_cvt_pk_f16_f32 v150, v30, v31
	v_cvt_pk_f16_f32 v151, v32, v33
	v_cvt_pk_f16_f32 v152, v26, v27
	v_cvt_pk_f16_f32 v153, v28, v29
.Lep1_12:
	global_store_dwordx4 v[148:149], v[150:153], off
	s_and_b64 vcc, exec, s[40:41]
	s_cbranch_vccnz .Lep0_13
	v_max_f32_e32 v150, 0, v22
	v_max_f32_e32 v151, 0, v23
	v_max_f32_e32 v152, 0, v24
	v_max_f32_e32 v153, 0, v25
	v_max_f32_e32 v154, 0, v18
	v_max_f32_e32 v155, 0, v19
	v_max_f32_e32 v156, 0, v20
	v_max_f32_e32 v157, 0, v21
	v_pk_mul_f32 v[150:151], v[150:151], v[150:151]
	v_pk_mul_f32 v[152:153], v[152:153], v[152:153]
	v_pk_mul_f32 v[154:155], v[154:155], v[154:155]
	v_pk_mul_f32 v[156:157], v[156:157], v[156:157]
	v_cvt_pk_f16_f32 v150, v150, v151
	v_cvt_pk_f16_f32 v151, v152, v153
	v_cvt_pk_f16_f32 v152, v154, v155
	v_cvt_pk_f16_f32 v153, v156, v157
	s_branch .Lep1_13
.Lep0_13:
	v_cvt_pk_f16_f32 v150, v22, v23
	v_cvt_pk_f16_f32 v151, v24, v25
	v_cvt_pk_f16_f32 v152, v18, v19
	v_cvt_pk_f16_f32 v153, v20, v21
.Lep1_13:
	global_store_dwordx4 v[148:149], v[150:153], off offset:256
	s_and_b64 vcc, exec, s[40:41]
	v_add_u32_e32 v16, 0xb0, v162
	v_ashrrev_i32_e32 v156, 31, v16
	v_mul_lo_u32 v164, s54, v156
	v_mul_lo_u32 v165, s55, v16
	v_mad_u64_u32 v[156:157], s[6:7], s54, v16, 0
	v_add3_u32 v157, v157, v164, v165
	v_lshl_add_u64 v[146:147], v[156:157], 1, v[146:147]
	s_cbranch_vccnz .Lep0_14
	v_max_f32_e32 v148, 0, v12
	v_max_f32_e32 v149, 0, v13
	v_max_f32_e32 v150, 0, v14
	v_max_f32_e32 v151, 0, v15
	v_max_f32_e32 v152, 0, v8
	v_max_f32_e32 v153, 0, v9
	v_max_f32_e32 v154, 0, v10
	v_max_f32_e32 v155, 0, v11
	v_pk_mul_f32 v[148:149], v[148:149], v[148:149]
	v_pk_mul_f32 v[150:151], v[150:151], v[150:151]
	v_pk_mul_f32 v[152:153], v[152:153], v[152:153]
	v_pk_mul_f32 v[154:155], v[154:155], v[154:155]
	v_cvt_pk_f16_f32 v148, v148, v149
	v_cvt_pk_f16_f32 v149, v150, v151
	v_cvt_pk_f16_f32 v150, v152, v153
	v_cvt_pk_f16_f32 v151, v154, v155
	s_branch .Lep1_14
.Lep0_14:
	v_cvt_pk_f16_f32 v148, v12, v13
	v_cvt_pk_f16_f32 v149, v14, v15
	v_cvt_pk_f16_f32 v150, v8, v9
	v_cvt_pk_f16_f32 v151, v10, v11
.Lep1_14:
	global_store_dwordx4 v[146:147], v[148:151], off
	s_and_b64 vcc, exec, s[40:41]
	s_cbranch_vccnz .Lep0_15
	v_max_f32_e32 v148, 0, v4
	v_max_f32_e32 v149, 0, v5
	v_max_f32_e32 v150, 0, v6
	v_max_f32_e32 v151, 0, v7
	v_max_f32_e32 v152, 0, v0
	v_max_f32_e32 v153, 0, v1
	v_max_f32_e32 v154, 0, v2
	v_max_f32_e32 v155, 0, v3
	v_pk_mul_f32 v[148:149], v[148:149], v[148:149]
	v_pk_mul_f32 v[150:151], v[150:151], v[150:151]
	v_pk_mul_f32 v[152:153], v[152:153], v[152:153]
	v_pk_mul_f32 v[154:155], v[154:155], v[154:155]
	v_cvt_pk_f16_f32 v148, v148, v149
	v_cvt_pk_f16_f32 v149, v150, v151
	v_cvt_pk_f16_f32 v150, v152, v153
	v_cvt_pk_f16_f32 v151, v154, v155
	s_branch .Lep1_15
.Lep0_15:
	v_cvt_pk_f16_f32 v148, v4, v5
	v_cvt_pk_f16_f32 v149, v6, v7
	v_cvt_pk_f16_f32 v150, v0, v1
	v_cvt_pk_f16_f32 v151, v2, v3
.Lep1_15:
	s_mov_b64 s[6:7], 0
	global_store_dwordx4 v[146:147], v[148:151], off offset:256
